# grid-barrier poll back-off s_sleep 2 -> 8 (fewer polls competing with the arriving atomics)
# speedup vs baseline: 1.0118x; 1.0076x over previous
; DI void grid_barrier(unsigned* ctr, unsigned target) {
;     __syncthreads();
;     if (threadIdx.x == 0) {
;         __builtin_amdgcn_fence(__ATOMIC_RELEASE, "agent");
;         __hip_atomic_fetch_add(ctr, 1u, __ATOMIC_RELAXED, __HIP_MEMORY_SCOPE_AGENT);
;         while (__hip_atomic_load(ctr, __ATOMIC_RELAXED, __HIP_MEMORY_SCOPE_AGENT) < target) __builtin_amdgcn_s_sleep(2);
;         __builtin_amdgcn_fence(__ATOMIC_ACQUIRE, "agent");
;     }
;     __syncthreads();
; }
.LBB0_1733:
	s_sleep 8
	global_load_dword v0, v173, s[12:13] sc1
	s_waitcnt vmcnt(0)
	v_cmp_gt_u32_e32 vcc, s2, v0
	s_cbranch_vccnz .LBB0_1733
